# natten: output-gate loads of 13 of 16 rows prefetched at the start of the last key-row step (v228-v253), copies at the old load sites
# speedup vs baseline: 1.0005x; 1.0005x over previous
.LBB0_501:
	s_lshl_b32 s46, s62, 1
	s_waitcnt vmcnt(3)
	v_lshl_add_u64 v[2:3], v[124:125], 0, s[46:47]
	v_lshlrev_b64 v[4:5], 13, v[140:141]
	v_lshl_add_u64 v[4:5], v[2:3], 0, v[4:5]
	v_lshlrev_b64 v[4:5], 13, v[142:143]
	v_lshl_add_u64 v[2:3], v[2:3], 0, v[4:5]
	global_load_dwordx2 v[6:7], v[2:3], off offset:160
	global_load_dwordx2 v[4:5], v[2:3], off offset:192
	s_nop 0
	global_load_dwordx2 v[2:3], v[2:3], off offset:224
	s_waitcnt vmcnt(3)
	v_mov_b64_e32 v[18:19], v[228:229]
	v_mov_b64_e32 v[20:21], v[230:231]
	v_mov_b64_e32 v[22:23], v[232:233]
	v_mov_b64_e32 v[24:25], v[234:235]
	v_mov_b64_e32 v[26:27], v[236:237]
	v_mov_b64_e32 v[28:29], v[238:239]
	v_mov_b64_e32 v[30:31], v[240:241]
	v_mov_b64_e32 v[32:33], v[242:243]
	v_mov_b64_e32 v[16:17], v[244:245]
	v_mov_b64_e32 v[14:15], v[246:247]
	v_mov_b64_e32 v[12:13], v[248:249]
	v_mov_b64_e32 v[10:11], v[250:251]
	v_mov_b64_e32 v[8:9], v[252:253]
	ds_bpermute_b32 v54, v173, v144
	s_waitcnt vmcnt(15)
	v_lshlrev_b32_e32 v63, 16, v18
	v_and_b32_e32 v18, 0xffff0000, v18
	v_or_b32_e32 v62, s62, v150
	v_lshlrev_b32_e32 v116, 1, v62
	s_waitcnt lgkmcnt(0)
	v_add_f32_e32 v56, v144, v54
	ds_bpermute_b32 v57, v174, v56
	v_lshl_add_u64 v[54:55], s[68:69], 0, v[138:139]
	v_lshl_add_u64 v[54:55], v[54:55], 0, s[50:51]
	s_add_i32 s61, s61, s33
	s_cmpk_gt_i32 s61, 0x7ff
	s_waitcnt lgkmcnt(0)
	v_add_f32_e32 v56, v56, v57
	v_div_scale_f32 v57, s[36:37], v56, v56, 1.0
	v_rcp_f32_e32 v64, v57
	v_div_scale_f32 v65, vcc, 1.0, v56, 1.0
	v_fma_f32 v70, -v57, v64, 1.0
	v_fmac_f32_e32 v64, v70, v64
	v_mul_f32_e32 v70, v65, v64
	v_fma_f32 v71, -v57, v70, v65
	v_fmac_f32_e32 v70, v71, v64
	v_fma_f32 v57, -v57, v70, v65
	v_div_fmas_f32 v57, v57, v64, v70
	v_div_fixup_f32 v64, v57, v56, 1.0
	v_mul_f32_e32 v56, v110, v64
	v_mul_f32_e32 v57, v111, v64
	v_mul_f32_e32 v56, v56, v63
	v_mul_f32_e32 v18, v57, v18
	v_cvt_pk_bf16_f32 v18, v56, v18
	v_mul_f32_e32 v56, v112, v64
	v_lshlrev_b32_e32 v57, 16, v19
	v_mul_f32_e32 v56, v56, v57
	v_mul_f32_e32 v57, v113, v64
	v_and_b32_e32 v19, 0xffff0000, v19
	v_mul_f32_e32 v19, v57, v19
	v_cvt_pk_bf16_f32 v19, v56, v19
	v_lshl_add_u64 v[56:57], v[54:55], 0, v[116:117]
	global_store_dwordx2 v[56:57], v[18:19], off
	v_mul_f32_e32 v18, v106, v64
	s_waitcnt vmcnt(15)
	v_lshlrev_b32_e32 v19, 16, v20
	v_mul_f32_e32 v18, v18, v19
	v_mul_f32_e32 v19, v107, v64
	v_and_b32_e32 v20, 0xffff0000, v20
	v_mul_f32_e32 v19, v19, v20
	v_cvt_pk_bf16_f32 v18, v18, v19
	v_mul_f32_e32 v19, v108, v64
	v_lshlrev_b32_e32 v20, 16, v21
	v_mul_f32_e32 v19, v19, v20
	v_mul_f32_e32 v20, v109, v64
	v_and_b32_e32 v21, 0xffff0000, v21
	v_mul_f32_e32 v20, v20, v21
	v_cvt_pk_bf16_f32 v19, v19, v20
	v_or_b32_e32 v20, 32, v116
	v_mov_b32_e32 v21, v117
	v_lshl_add_u64 v[56:57], v[54:55], 0, v[20:21]
	global_store_dwordx2 v[56:57], v[18:19], off
	v_mul_f32_e32 v18, v102, v64
	s_waitcnt vmcnt(15)
	v_lshlrev_b32_e32 v19, 16, v22
	v_mul_f32_e32 v18, v18, v19
	v_mul_f32_e32 v19, v103, v64
	v_and_b32_e32 v22, 0xffff0000, v22
	v_mul_f32_e32 v19, v19, v22
	v_cvt_pk_bf16_f32 v18, v18, v19
	v_mul_f32_e32 v19, v104, v64
	v_lshlrev_b32_e32 v22, 16, v23
	v_mul_f32_e32 v19, v19, v22
	v_mul_f32_e32 v22, v105, v64
	v_and_b32_e32 v23, 0xffff0000, v23
	v_mul_f32_e32 v22, v22, v23
	v_cvt_pk_bf16_f32 v19, v19, v22
	v_or_b32_e32 v22, 64, v116
	v_mov_b32_e32 v23, v117
	v_lshl_add_u64 v[56:57], v[54:55], 0, v[22:23]
	global_store_dwordx2 v[56:57], v[18:19], off
	v_mul_f32_e32 v18, v98, v64
	s_waitcnt vmcnt(15)
	v_lshlrev_b32_e32 v19, 16, v24
	v_mul_f32_e32 v18, v18, v19
	v_mul_f32_e32 v19, v99, v64
	v_and_b32_e32 v24, 0xffff0000, v24
	v_mul_f32_e32 v19, v19, v24
	v_cvt_pk_bf16_f32 v18, v18, v19
	v_mul_f32_e32 v19, v100, v64
	v_lshlrev_b32_e32 v24, 16, v25
	v_mul_f32_e32 v19, v19, v24
	v_mul_f32_e32 v24, v101, v64
	v_and_b32_e32 v25, 0xffff0000, v25
	v_mul_f32_e32 v24, v24, v25
	v_cvt_pk_bf16_f32 v19, v19, v24
	v_or_b32_e32 v24, 0x60, v116
	v_mov_b32_e32 v25, v117
	v_lshl_add_u64 v[56:57], v[54:55], 0, v[24:25]
	global_store_dwordx2 v[56:57], v[18:19], off
	v_mul_f32_e32 v18, v94, v64
	s_waitcnt vmcnt(15)
	v_lshlrev_b32_e32 v19, 16, v26
	v_mul_f32_e32 v18, v18, v19
	v_mul_f32_e32 v19, v95, v64
	v_and_b32_e32 v26, 0xffff0000, v26
	v_mul_f32_e32 v19, v19, v26
	v_cvt_pk_bf16_f32 v18, v18, v19
	v_mul_f32_e32 v19, v96, v64
	v_lshlrev_b32_e32 v26, 16, v27
	v_mul_f32_e32 v19, v19, v26
	v_mul_f32_e32 v26, v97, v64
	v_and_b32_e32 v27, 0xffff0000, v27
	v_mul_f32_e32 v26, v26, v27
	v_cvt_pk_bf16_f32 v19, v19, v26
	v_or_b32_e32 v26, 0x80, v116
	v_mov_b32_e32 v27, v117
	v_lshl_add_u64 v[56:57], v[54:55], 0, v[26:27]
	global_store_dwordx2 v[56:57], v[18:19], off
	v_mul_f32_e32 v18, v90, v64
	s_waitcnt vmcnt(15)
	v_lshlrev_b32_e32 v19, 16, v28
	v_mul_f32_e32 v18, v18, v19
	v_mul_f32_e32 v19, v91, v64
	v_and_b32_e32 v28, 0xffff0000, v28
	v_mul_f32_e32 v19, v19, v28
	v_cvt_pk_bf16_f32 v18, v18, v19
	v_mul_f32_e32 v19, v92, v64
	v_lshlrev_b32_e32 v28, 16, v29
	v_mul_f32_e32 v19, v19, v28
	v_mul_f32_e32 v28, v93, v64
	v_and_b32_e32 v29, 0xffff0000, v29
	v_mul_f32_e32 v28, v28, v29
	v_cvt_pk_bf16_f32 v19, v19, v28
	v_or_b32_e32 v28, 0xa0, v116
	v_mov_b32_e32 v29, v117
	v_lshl_add_u64 v[56:57], v[54:55], 0, v[28:29]
	global_store_dwordx2 v[56:57], v[18:19], off
	v_mul_f32_e32 v18, v86, v64
	s_waitcnt vmcnt(15)
	v_lshlrev_b32_e32 v19, 16, v30
	v_mul_f32_e32 v18, v18, v19
	v_mul_f32_e32 v19, v87, v64
	v_and_b32_e32 v30, 0xffff0000, v30
	v_mul_f32_e32 v19, v19, v30
	v_cvt_pk_bf16_f32 v18, v18, v19
	v_mul_f32_e32 v19, v88, v64
	v_lshlrev_b32_e32 v30, 16, v31
	v_mul_f32_e32 v19, v19, v30
	v_mul_f32_e32 v30, v89, v64
	v_and_b32_e32 v31, 0xffff0000, v31
	v_mul_f32_e32 v30, v30, v31
	v_cvt_pk_bf16_f32 v19, v19, v30
	v_or_b32_e32 v30, 0xc0, v116
	v_mov_b32_e32 v31, v117
	v_lshl_add_u64 v[56:57], v[54:55], 0, v[30:31]
	global_store_dwordx2 v[56:57], v[18:19], off
	v_mul_f32_e32 v18, v82, v64
	s_waitcnt vmcnt(15)
	v_lshlrev_b32_e32 v19, 16, v32
	v_mul_f32_e32 v18, v18, v19
	v_mul_f32_e32 v19, v83, v64
	v_and_b32_e32 v32, 0xffff0000, v32
	v_mul_f32_e32 v19, v19, v32
	v_cvt_pk_bf16_f32 v18, v18, v19
	ds_bpermute_b32 v19, v173, v145
	v_mul_f32_e32 v32, v84, v64
	v_lshlrev_b32_e32 v56, 16, v33
	v_mul_f32_e32 v32, v32, v56
	v_mul_f32_e32 v56, v85, v64
	s_waitcnt lgkmcnt(0)
	v_add_f32_e32 v57, v145, v19
	ds_bpermute_b32 v62, v174, v57
	v_and_b32_e32 v19, 0xffff0000, v33
	v_mul_f32_e32 v19, v56, v19
	v_cvt_pk_bf16_f32 v19, v32, v19
	v_or_b32_e32 v32, 0xe0, v116
	s_waitcnt lgkmcnt(0)
	v_add_f32_e32 v56, v57, v62
	v_div_scale_f32 v57, s[36:37], v56, v56, 1.0
	v_rcp_f32_e32 v62, v57
	v_mov_b32_e32 v33, v117
	v_lshl_add_u64 v[54:55], v[54:55], 0, v[32:33]
	global_store_dwordx2 v[54:55], v[18:19], off
	v_fma_f32 v18, -v57, v62, 1.0
	v_fmac_f32_e32 v62, v18, v62
	v_div_scale_f32 v18, vcc, 1.0, v56, 1.0
	v_mul_f32_e32 v19, v18, v62
	v_fma_f32 v54, -v57, v19, v18
	v_fmac_f32_e32 v19, v54, v62
	v_fma_f32 v18, -v57, v19, v18
	v_div_fmas_f32 v18, v18, v62, v19
	v_div_fixup_f32 v56, v18, v56, 1.0
	v_mul_f32_e32 v54, v74, v56
	s_waitcnt vmcnt(15)
	v_lshlrev_b32_e32 v55, 16, v16
	v_mul_f32_e32 v54, v54, v55
	v_mul_f32_e32 v55, v75, v56
	v_and_b32_e32 v16, 0xffff0000, v16
	v_mul_f32_e32 v16, v55, v16
	v_cvt_pk_bf16_f32 v16, v54, v16
	v_mul_f32_e32 v54, v76, v56
	v_lshlrev_b32_e32 v55, 16, v17
	v_lshl_add_u64 v[18:19], s[68:69], 0, v[136:137]
	v_mul_f32_e32 v54, v54, v55
	v_mul_f32_e32 v55, v77, v56
	v_and_b32_e32 v17, 0xffff0000, v17
	v_lshl_add_u64 v[18:19], v[18:19], 0, s[50:51]
	v_mul_f32_e32 v17, v55, v17
	v_cvt_pk_bf16_f32 v17, v54, v17
	v_lshl_add_u64 v[54:55], v[18:19], 0, v[116:117]
	global_store_dwordx2 v[54:55], v[16:17], off
	v_mul_f32_e32 v16, v66, v56
	s_waitcnt vmcnt(15)
	v_lshlrev_b32_e32 v17, 16, v14
	v_mul_f32_e32 v16, v16, v17
	v_mul_f32_e32 v17, v67, v56
	v_and_b32_e32 v14, 0xffff0000, v14
	v_mul_f32_e32 v14, v17, v14
	v_cvt_pk_bf16_f32 v14, v16, v14
	v_mul_f32_e32 v16, v68, v56
	v_lshlrev_b32_e32 v17, 16, v15
	v_mul_f32_e32 v16, v16, v17
	v_mul_f32_e32 v17, v69, v56
	v_and_b32_e32 v15, 0xffff0000, v15
	v_mul_f32_e32 v15, v17, v15
	v_cvt_pk_bf16_f32 v15, v16, v15
	v_lshl_add_u64 v[16:17], v[18:19], 0, v[20:21]
	global_store_dwordx2 v[16:17], v[14:15], off
	v_mul_f32_e32 v14, v58, v56
	s_waitcnt vmcnt(15)
	v_lshlrev_b32_e32 v15, 16, v12
	v_mul_f32_e32 v14, v14, v15
	v_mul_f32_e32 v15, v59, v56
	v_and_b32_e32 v12, 0xffff0000, v12
	v_mul_f32_e32 v12, v15, v12
	v_cvt_pk_bf16_f32 v12, v14, v12
	v_mul_f32_e32 v14, v60, v56
	v_lshlrev_b32_e32 v15, 16, v13
	v_mul_f32_e32 v14, v14, v15
	v_mul_f32_e32 v15, v61, v56
	v_and_b32_e32 v13, 0xffff0000, v13
	v_mul_f32_e32 v13, v15, v13
	v_cvt_pk_bf16_f32 v13, v14, v13
	v_lshl_add_u64 v[14:15], v[18:19], 0, v[22:23]
	global_store_dwordx2 v[14:15], v[12:13], off
	v_mul_f32_e32 v12, v50, v56
	s_waitcnt vmcnt(15)
	v_lshlrev_b32_e32 v13, 16, v10
	v_mul_f32_e32 v12, v12, v13
	v_mul_f32_e32 v13, v51, v56
	v_and_b32_e32 v10, 0xffff0000, v10
	v_mul_f32_e32 v10, v13, v10
	v_cvt_pk_bf16_f32 v10, v12, v10
	v_mul_f32_e32 v12, v52, v56
	v_lshlrev_b32_e32 v13, 16, v11
	v_mul_f32_e32 v12, v12, v13
	v_mul_f32_e32 v13, v53, v56
	v_and_b32_e32 v11, 0xffff0000, v11
	v_mul_f32_e32 v11, v13, v11
	v_cvt_pk_bf16_f32 v11, v12, v11
	v_lshl_add_u64 v[12:13], v[18:19], 0, v[24:25]
	global_store_dwordx2 v[12:13], v[10:11], off
	v_mul_f32_e32 v10, v46, v56
	s_waitcnt vmcnt(15)
	v_lshlrev_b32_e32 v11, 16, v8
	v_mul_f32_e32 v10, v10, v11
	v_mul_f32_e32 v11, v47, v56
	v_and_b32_e32 v8, 0xffff0000, v8
	v_mul_f32_e32 v8, v11, v8
	v_cvt_pk_bf16_f32 v8, v10, v8
	v_mul_f32_e32 v10, v48, v56
	v_lshlrev_b32_e32 v11, 16, v9
	v_mul_f32_e32 v10, v10, v11
	v_mul_f32_e32 v11, v49, v56
	v_and_b32_e32 v9, 0xffff0000, v9
	v_mul_f32_e32 v9, v11, v9
	v_cvt_pk_bf16_f32 v9, v10, v9
	v_lshl_add_u64 v[10:11], v[18:19], 0, v[26:27]
	global_store_dwordx2 v[10:11], v[8:9], off
	v_mul_f32_e32 v8, v42, v56
	s_waitcnt vmcnt(15)
	v_lshlrev_b32_e32 v9, 16, v6
	v_mul_f32_e32 v8, v8, v9
	v_mul_f32_e32 v9, v43, v56
	v_and_b32_e32 v6, 0xffff0000, v6
	v_mul_f32_e32 v6, v9, v6
	v_cvt_pk_bf16_f32 v6, v8, v6
	v_mul_f32_e32 v8, v44, v56
	v_lshlrev_b32_e32 v9, 16, v7
	v_mul_f32_e32 v8, v8, v9
	v_mul_f32_e32 v9, v45, v56
	v_and_b32_e32 v7, 0xffff0000, v7
	v_mul_f32_e32 v7, v9, v7
	v_cvt_pk_bf16_f32 v7, v8, v7
	v_lshl_add_u64 v[8:9], v[18:19], 0, v[28:29]
	global_store_dwordx2 v[8:9], v[6:7], off
	v_mul_f32_e32 v6, v38, v56
	s_waitcnt vmcnt(15)
	v_lshlrev_b32_e32 v7, 16, v4
	v_mul_f32_e32 v6, v6, v7
	v_mul_f32_e32 v7, v39, v56
	v_and_b32_e32 v4, 0xffff0000, v4
	v_mul_f32_e32 v4, v7, v4
	v_cvt_pk_bf16_f32 v4, v6, v4
	v_mul_f32_e32 v6, v40, v56
	v_lshlrev_b32_e32 v7, 16, v5
	v_mul_f32_e32 v6, v6, v7
	v_mul_f32_e32 v7, v41, v56
	v_and_b32_e32 v5, 0xffff0000, v5
	v_mul_f32_e32 v5, v7, v5
	v_cvt_pk_bf16_f32 v5, v6, v5
	v_lshl_add_u64 v[6:7], v[18:19], 0, v[30:31]
	global_store_dwordx2 v[6:7], v[4:5], off
	v_mul_f32_e32 v4, v34, v56
	s_waitcnt vmcnt(15)
	v_lshlrev_b32_e32 v5, 16, v2
	v_mul_f32_e32 v4, v4, v5
	v_mul_f32_e32 v5, v35, v56
	v_and_b32_e32 v2, 0xffff0000, v2
	v_mul_f32_e32 v2, v5, v2
	v_cvt_pk_bf16_f32 v2, v4, v2
	v_mul_f32_e32 v4, v36, v56
	v_lshlrev_b32_e32 v5, 16, v3
	v_mul_f32_e32 v4, v4, v5
	v_mul_f32_e32 v5, v37, v56
	v_and_b32_e32 v3, 0xffff0000, v3
	v_mul_f32_e32 v3, v5, v3
	v_cvt_pk_bf16_f32 v3, v4, v3
	v_lshl_add_u64 v[4:5], v[18:19], 0, v[32:33]
	global_store_dwordx2 v[4:5], v[2:3], off
	s_cbranch_scc1 .LBB0_519

.Lnat_bz:
	s_lshl_b32 s98, s62, 1
	s_mov_b32 s99, 0
	v_lshl_add_u64 v[252:253], v[124:125], 0, s[98:99]
	v_lshlrev_b64 v[242:243], 13, v[140:141]
	v_lshl_add_u64 v[242:243], v[252:253], 0, v[242:243]
	global_load_dwordx2 v[228:229], v[242:243], off
	global_load_dwordx2 v[230:231], v[242:243], off offset:32
	global_load_dwordx2 v[232:233], v[242:243], off offset:64
	global_load_dwordx2 v[234:235], v[242:243], off offset:96
	global_load_dwordx2 v[236:237], v[242:243], off offset:128
	global_load_dwordx2 v[238:239], v[242:243], off offset:160
	global_load_dwordx2 v[240:241], v[242:243], off offset:192
	global_load_dwordx2 v[242:243], v[242:243], off offset:224
	v_lshlrev_b64 v[250:251], 13, v[142:143]
	v_lshl_add_u64 v[252:253], v[252:253], 0, v[250:251]
	global_load_dwordx2 v[244:245], v[252:253], off
	global_load_dwordx2 v[246:247], v[252:253], off offset:32
	global_load_dwordx2 v[248:249], v[252:253], off offset:64
	global_load_dwordx2 v[250:251], v[252:253], off offset:96
	global_load_dwordx2 v[252:253], v[252:253], off offset:128
	s_branch .LBB0_512
